# v34 + stick-breaking attention phase: one static s_setprio 1 for waves 4-7 before the unit loop (reset after)
# baseline (speedup 1.0000x reference)
.LBB0_872:
	s_or_b64 exec, exec, s[0:1]
	v_mov_b32_e32 v16, v161
	s_waitcnt lgkmcnt(0)
	s_barrier
	s_and_b64 vcc, exec, s[76:77]
	v_readfirstlane_b32 s0, v16
	s_mov_b32 s76, s94
	v_readlane_b32 s77, v234, 42
	s_cbranch_vccz .LBB0_927
	v_bfe_u32 v18, v16, 4, 2
	v_and_b32_e32 v134, 15, v16
	v_lshlrev_b32_e32 v135, 2, v18
	v_mov_b32_e32 v13, 0x3f80
	v_cmp_lt_u32_e32 vcc, v135, v134
	v_or_b32_e32 v0, 50, v135
	v_or_b32_e32 v3, 48, v134
	v_cndmask_b32_e64 v12, v13, 0, vcc
	v_or_b32_e32 v1, 49, v135
	v_cmp_lt_u32_e32 vcc, v0, v3
	s_mov_b32 s1, 0x5040100
	v_or_b32_e32 v4, 34, v135
	v_cndmask_b32_e64 v0, v13, 0, vcc
	v_cmp_lt_u32_e32 vcc, v1, v3
	v_or_b32_e32 v6, 32, v134
	v_or_b32_e32 v5, 33, v135
	v_cndmask_b32_e64 v1, v13, 0, vcc
	v_perm_b32 v2, v1, v12, s1
	v_or_b32_e32 v1, 51, v135
	v_cmp_lt_u32_e32 vcc, v1, v3
	v_or_b32_e32 v8, 18, v135
	v_or_b32_e32 v11, 16, v134
	v_cndmask_b32_e64 v1, v13, 0, vcc
	v_cmp_lt_u32_e32 vcc, v4, v6
	v_or_b32_e32 v9, 17, v135
	v_or_b32_e32 v14, 2, v135
	v_cndmask_b32_e64 v7, v13, 0, vcc
	v_cmp_lt_u32_e32 vcc, v5, v6
	v_or_b32_e32 v5, 35, v135
	v_or_b32_e32 v15, 1, v135
	v_cndmask_b32_e64 v4, v13, 0, vcc
	v_cmp_lt_u32_e32 vcc, v5, v6
	v_perm_b32 v4, v4, v12, s1
	v_perm_b32 v3, v1, v0, s1
	v_cndmask_b32_e64 v5, v13, 0, vcc
	v_cmp_lt_u32_e32 vcc, v8, v11
	v_perm_b32 v5, v5, v7, s1
	v_ashrrev_i32_e32 v138, 3, v16
	v_cndmask_b32_e64 v8, v13, 0, vcc
	v_cmp_lt_u32_e32 vcc, v9, v11
	v_and_b32_e32 v19, 7, v16
	v_mov_b32_e32 v137, 0
	v_cndmask_b32_e64 v9, v13, 0, vcc
	v_perm_b32 v10, v9, v12, s1
	v_or_b32_e32 v9, 19, v135
	v_cmp_lt_u32_e32 vcc, v9, v11
	s_ashr_i32 s0, s0, 6
	v_lshlrev_b32_e32 v20, 4, v19
	v_cndmask_b32_e64 v9, v13, 0, vcc
	v_cmp_lt_u32_e32 vcc, v14, v134
	v_perm_b32 v11, v9, v8, s1
	v_and_b32_e32 v17, 63, v16
	v_cndmask_b32_e64 v14, v13, 0, vcc
	v_cmp_lt_u32_e32 vcc, v15, v134
	s_lshl_b32 s3, s0, 5
	v_cmp_gt_i32_e64 s[4:5], 16, v16
	v_cndmask_b32_e64 v15, v13, 0, vcc
	v_perm_b32 v12, v15, v12, s1
	v_or_b32_e32 v15, 3, v135
	v_cmp_lt_u32_e32 vcc, v15, v134
	v_lshl_add_u32 v156, v16, 2, 0
	s_lshl_b32 s0, s0, 2
	v_cndmask_b32_e64 v13, v13, 0, vcc
	v_perm_b32 v13, v13, v14, s1
	s_movk_i32 s1, 0x90
	v_mul_lo_u32 v21, v138, s1
	v_add3_u32 v157, v21, v20, 0
	v_and_b32_e32 v16, 48, v16
	v_mov_b32_e32 v21, v137
	v_ashrrev_i32_e32 v139, 31, v138
	s_add_i32 s22, s0, 0
	v_add_u32_e32 v158, 0, v16
	v_cmp_eq_u32_e64 s[6:7], 0, v17
	v_lshl_add_u64 v[16:17], s[84:85], 0, v[20:21]
	s_mov_b64 s[0:1], 0x1c400100
	v_lshl_add_u64 v[142:143], v[16:17], 0, s[0:1]
	v_readlane_b32 s0, v234, 0
	v_lshlrev_b64 v[16:17], 12, v[138:139]
	v_readlane_b32 s1, v234, 1
	v_or_b32_e32 v16, v16, v20
	v_mov_b32_e32 v6, 0x3f803f80
	v_lshlrev_b32_e32 v136, 3, v18
	v_lshlrev_b32_e32 v18, 3, v19
	s_mov_b32 s8, s0
	s_lshl_b32 s23, s0, 2
	v_lshl_add_u64 v[16:17], s[84:85], 0, v[16:17]
	s_mov_b64 s[0:1], 0x18480000
	s_mov_b32 s65, 0
	v_mov_b32_e32 v0, v137
	v_mov_b32_e32 v1, v137
	s_mov_b32 s52, 0x3f803f80
	v_mov_b32_e32 v7, v6
	v_mov_b32_e32 v8, v137
	v_mov_b32_e32 v9, v137
	v_mov_b32_e32 v14, v6
	v_mov_b32_e32 v15, v6
	v_add_u32_e32 v159, 0, v136
	v_lshl_add_u64 v[140:141], s[68:69], 0, v[136:137]
	v_mul_u32_u24_e32 v164, 0x90, v134
	s_lshl_b32 s42, s82, 2
	v_lshl_add_u64 v[144:145], v[16:17], 0, s[0:1]
	v_lshlrev_b32_e32 v146, 1, v136
	s_mov_b32 s43, 0xc316199a
	v_mov_b32_e32 v147, v137
	v_lshlrev_b32_e32 v136, 1, v18
	s_mov_b32 s47, s8
	v_readfirstlane_b32 s98, v185
	s_nop 3
	s_cmp_ge_u32 s98, 4
	s_cbranch_scc0 .Lsb_prio
	s_setprio 1

.LBB0_927:
	s_setprio 0
	s_waitcnt vmcnt(0)
	s_waitcnt lgkmcnt(0)
	s_barrier
	s_and_saveexec_b64 s[0:1], s[78:79]
	s_xor_b64 s[0:1], exec, s[0:1]
	s_cbranch_execz .LBB0_980
	s_add_i32 s3, 0, 0x22800
	v_mov_b32_e32 v0, s3
	s_waitcnt vmcnt(0) expcnt(0) lgkmcnt(0)
	ds_read_b32 v2, v0
	s_add_i32 s3, 0, 0x22804
	v_mov_b32_e32 v0, s3
	ds_read_b32 v0, v0
	s_waitcnt lgkmcnt(1)
	v_cmp_ne_u32_e32 vcc, 0, v2
	s_cbranch_vccnz .LBB0_943
	s_add_u32 s4, s84, 0x4200
	s_addc_u32 s5, s85, 0
	s_add_u32 s6, s84, 0x4400
	s_addc_u32 s7, s85, 0
	s_add_u32 s8, s84, 0x4500
	s_addc_u32 s9, s85, 0
	s_add_u32 s10, s84, 0x4600
	s_addc_u32 s11, s85, 0
	s_add_u32 s12, s84, 0x4700
	s_addc_u32 s13, s85, 0
	s_add_u32 s14, s84, 0x4800
	s_addc_u32 s15, s85, 0
	s_add_u32 s16, s84, 0x4900
	s_addc_u32 s17, s85, 0
	s_add_u32 s18, s84, 0x4a00
	s_addc_u32 s19, s85, 0
	s_add_u32 s20, s84, 0x4b00
	s_addc_u32 s21, s85, 0
	s_add_u32 s24, s84, 0x4c00
	s_addc_u32 s25, s85, 0
	s_add_u32 s26, s84, 0x4d00
	s_addc_u32 s27, s85, 0
	s_add_u32 s28, s84, 0x4e00
	s_addc_u32 s29, s85, 0
	s_add_u32 s30, s84, 0x4f00
	s_addc_u32 s31, s85, 0
	s_add_u32 s34, s84, 0x5000
	s_addc_u32 s35, s85, 0
	s_add_u32 s36, s84, 0x5100
	s_addc_u32 s37, s85, 0
	s_add_u32 s38, s84, 0x5200
	v_readlane_b32 s3, v234, 2
	s_addc_u32 s39, s85, 0
	s_mul_i32 s3, s83, s3
	s_add_u32 s40, s84, 0x5300
	s_mul_i32 s3, s3, s82
	s_addc_u32 s41, s85, 0
	s_mov_b32 s22, 1
	v_mov_b32_e32 v16, 0
	s_branch .LBB0_931
